# phase entry: from the second phase on the kernarg spill lanes are not rewritten; the 4 live kernarg loads issued together (one wait)
# baseline (speedup 1.0000x reference)
.Lpl_skip:
	s_mov_b32 s48, s93
	s_mov_b64 s[0:1], s[90:91]
	s_mov_b64 s[4:5], 0
	s_cmp_gt_i32 s14, 0
	s_cbranch_scc0 .Lpe_slow
	s_load_dwordx2 s[2:3], s[0:1], 0xb0
	s_load_dwordx8 s[60:67], s[0:1], 0x60
	s_load_dwordx4 s[80:83], s[0:1], 0xa0
	s_load_dwordx8 s[52:59], s[0:1], 0x80
	s_mov_b64 s[40:41], -1
	s_mov_b64 s[10:11], 0
	s_mov_b64 s[0:1], 0
	s_waitcnt lgkmcnt(0)
	s_add_u32 s8, s2, s4
	s_addc_u32 s9, s3, s5
	s_branch .Lpe_join
.Lpe_slow:
	s_load_dwordx2 s[2:3], s[0:1], 0xb0
	s_load_dwordx16 s[52:67], s[0:1], 0x0
	s_mov_b64 s[40:41], -1
	s_mov_b64 s[10:11], 0
	s_waitcnt lgkmcnt(0)
	s_add_u32 s8, s2, s4
	v_writelane_b32 v253, s52, 63
	s_nop 1
	v_writelane_b32 v254, s53, 0
	v_writelane_b32 v254, s54, 1
	v_writelane_b32 v254, s55, 2
	v_writelane_b32 v254, s56, 3
	v_writelane_b32 v254, s57, 4
	v_writelane_b32 v254, s58, 5
	v_writelane_b32 v254, s59, 6
	v_writelane_b32 v254, s60, 7
	v_writelane_b32 v254, s61, 8
	v_writelane_b32 v254, s62, 9
	v_writelane_b32 v254, s63, 10
	v_writelane_b32 v254, s64, 11
	v_writelane_b32 v254, s65, 12
	v_writelane_b32 v254, s66, 13
	v_writelane_b32 v254, s67, 14
	s_load_dwordx16 s[52:67], s[0:1], 0x40
	s_waitcnt lgkmcnt(0)
	v_writelane_b32 v254, s52, 15
	s_nop 1
	v_writelane_b32 v254, s53, 16
	v_writelane_b32 v254, s54, 17
	v_writelane_b32 v254, s55, 18
	v_writelane_b32 v254, s56, 19
	v_writelane_b32 v254, s57, 20
	v_writelane_b32 v254, s58, 21
	v_writelane_b32 v254, s59, 22
	v_writelane_b32 v254, s60, 23
	v_writelane_b32 v254, s61, 24
	v_writelane_b32 v254, s62, 25
	v_writelane_b32 v254, s63, 26
	v_writelane_b32 v254, s64, 27
	v_writelane_b32 v254, s65, 28
	v_writelane_b32 v254, s66, 29
	v_writelane_b32 v254, s67, 30
	s_load_dwordx4 s[80:83], s[0:1], 0xa0
	s_load_dwordx8 s[52:59], s[0:1], 0x80
	s_mov_b64 s[0:1], 0
	s_waitcnt lgkmcnt(0)
	v_writelane_b32 v254, s52, 31
	s_nop 1
	v_writelane_b32 v254, s53, 32
	v_writelane_b32 v254, s54, 33
	v_writelane_b32 v254, s55, 34
	v_writelane_b32 v254, s56, 35
	v_writelane_b32 v254, s57, 36
	v_writelane_b32 v254, s58, 37
	v_writelane_b32 v254, s59, 38
	v_writelane_b32 v254, s2, 39
	s_addc_u32 s9, s3, s5
	s_nop 0
	v_writelane_b32 v254, s3, 40
.Lpe_join:
	s_add_u32 s2, s8, 0x300000
	s_addc_u32 s3, s9, 0
	s_cmp_lt_i32 s14, 1
	s_cbranch_scc1 .LBB0_18
	s_cmp_eq_u32 s14, 2
	s_mov_b64 s[0:1], -1
	s_cbranch_scc0 .LBB0_17
	v_mov_b32_e32 v0, v203
	s_lshl_b32 s0, s48, 6
	v_readlane_b32 s1, v253, 0
	s_add_i32 s0, s0, s1
	v_add_u32_e32 v0, s0, v0
	v_cmp_gt_i32_e32 vcc, s78, v0
	s_and_saveexec_b64 s[0:1], vcc
	s_cbranch_execz .LBB0_16
	v_readlane_b32 s40, v253, 1
	v_readlane_b32 s41, v253, 2
	s_load_dword s7, s[40:41], 0x0
	s_add_u32 s40, s8, 0x100000
	v_readlane_b32 s52, v253, 63
	s_addc_u32 s41, s9, 0
	s_lshl_b64 s[42:43], s[4:5], 2
	s_waitcnt lgkmcnt(0)
	s_lshl_b32 s7, s7, 9
	v_readlane_b32 s64, v254, 11
	v_readlane_b32 s65, v254, 12
	s_add_u32 s42, s64, s42
	s_addc_u32 s43, s65, s43
	s_mov_b64 s[46:47], 0
	v_readlane_b32 s53, v254, 0
	v_readlane_b32 s54, v254, 1
	v_readlane_b32 s55, v254, 2
	v_readlane_b32 s56, v254, 3
	v_readlane_b32 s57, v254, 4
	v_readlane_b32 s58, v254, 5
	v_readlane_b32 s59, v254, 6
	v_readlane_b32 s60, v254, 7
	v_readlane_b32 s61, v254, 8
	v_readlane_b32 s62, v254, 9
	v_readlane_b32 s63, v254, 10
	v_readlane_b32 s66, v254, 13
	v_readlane_b32 s67, v254, 14
